# attention: V tile fetched in natural key order so P needs no permlane swaps; dropped canonicalizing max ops
# baseline (speedup 1.0000x reference)
; #define LAS __attribute__((address_space(3)))
; #define WAITBAR(N) asm volatile("s_waitcnt vmcnt(" #N ") lgkmcnt(0)\n\ts_barrier" ::: "memory")
; __device__ __forceinline__ float qkt(f32x16& p0, f32x16& p1, const LAS char* Ks, const bf16x8* qr, int r32, int hi, int dlt, float cL, float cR, const LAS float* tabL) {
;     ...
;     for (int d0 = 0; d0 < 4; ++d0) { const int cb = d0 * 32 + hi * 16;
;         b0[d0] = *(const LAS bf16x8*)(Ks + KSWZ64(r32, cb)); b1[d0] = *(const LAS bf16x8*)(Ks + KSWZ64(32 + r32, cb)); }
;     if (dlt <= -191 || dlt >= 159) {
;         const f32x16 z = f32x16{};
; __device__ __forceinline__ void attn_unit(int b, int h, int qb, const bf16_t* __restrict__ proj, const float* __restrict__ btab, float lam, float outscale,
;                                           const float* __restrict__ gain, float* o1scr, bf16_t* merged, LAS char* lds) {
;     ...
;     unsigned koff, voffA, voffB;
;     { const int row = wid * 8 + (lane >> 3), c16 = (lane & 7) ^ ((row >> 1) & 7); koff = (unsigned)((row * LD + c16 * 8) * 2);
;       const int within = lane & 31;
; #pragma unroll
;       for (int i = 0; i < 2; ++i) { const int sub = (2 * wid + i) * 2 + (lane >> 5); const int kk = (sub >> 2) * 8 + (within >> 2);
;           const int k = (kk & ~0xC) | ((kk & 4) << 1) | ((kk & 8) >> 1), c = (sub & 3) * 32 + (within & 3) * 8;
;           const unsigned o = (unsigned)((k * LD + c) * 2); if (i == 0) voffA = o; else voffB = o; } }
;     const int vb0 = (int)(unsigned)(uintptr_t)V_lds + v_rd_base(lane);
;     const bf16_t* Vh = proj + rowbase * LD + OV + h * 128;
; #pragma unroll 1
;     for (int s = 0; s < 2; ++s) {
;         const int hq = 2 * h + s;
;         const bf16_t* Kh = proj + rowbase * LD + OKK + hq * 64;
;         const bf16_t* Qw = proj + (rowbase + qw + r32) * LD + OQ + hq * 64 + hi * 8;
;         float m_reg = -1e30f, l_reg = 0; f32x16 o[4]; bf16x8 qr[4];
; #pragma unroll
;         for (int d0 = 0; d0 < 4; ++d0) { o[d0] = f32x16{}; qr[d0] = *(const bf16x8*)(Qw + d0 * 16); }
;     ...
;         f32x16 pA0, pA1, pB0, pB1; float mnA, mnB, alA, alB, bo; bf16x8 pa0, pa1, pa2, pa3; constexpr int NT = T / 64;
;         asm volatile("s_waitcnt vmcnt(0) lgkmcnt(0)" ::: "memory"); __syncthreads();
;         DMA_TILE(0, 0); DMA_TILE(1, 1);
;         WAITBAR(3);
;         bo = qkt(pA0, pA1, K_lds, qr, r32, hi, 0 - qw, cL, cR, tabL); partialSM(pA0, pA1, m_reg, mnA, alA, bo);
.LBB0_187:
	s_or_b32 s24, s6, s48
	s_lshl_b64 s[2:3], s[24:25], 1
	v_lshl_add_u64 v[2:3], v[190:191], 0, s[2:3]
	s_add_u32 s2, s36, s2
	s_addc_u32 s3, s37, s3
	flat_load_dwordx4 v[142:145], v[2:3]
	flat_load_dwordx4 v[138:141], v[2:3] offset:32
	flat_load_dwordx4 v[134:137], v[2:3] offset:64
	flat_load_dwordx4 v[130:133], v[2:3] offset:96
	v_lshl_add_u64 v[184:185], s[2:3], 0, v[186:187]
	s_xor_b64 s[2:3], s[0:1], -1
	s_mov_b64 s[6:7], 0x800
	v_lshl_add_u64 v[184:185], v[184:185], 0, s[6:7]
	v_mov_b64_e32 v[250:251], v[192:193]
	v_mov_b64_e32 v[246:247], v[194:195]
	s_mov_b32 s6, 0xc8000
	s_mov_b32 s7, 0
	v_readfirstlane_b32 s67, v222
	v_add_u32_e32 v239, v226, v227
	v_add_u32_e32 v240, v226, v228
	v_add_u32_e32 v241, v226, v229
	v_add_u32_e32 v242, v226, v230
	s_lshr_b32 s67, s67, 8
	v_add_u32_e32 v239, 0x14000, v239
	v_add_u32_e32 v240, 0x14000, v240
	v_add_u32_e32 v241, 0x14000, v241
	v_add_u32_e32 v242, 0x14000, v242
	v_mov_b32_e32 v243, v215
	v_bfe_u32 v244, v222, 4, 1
	v_bfe_u32 v249, v222, 6, 1
	v_sub_u32_e32 v244, v249, v244
	v_mul_i32_i24_e32 v244, 0xc800, v244
	v_ashrrev_i32_e32 v245, 31, v244
	v_lshl_add_u64 v[250:251], v[250:251], 0, v[244:245]
	v_lshl_add_u64 v[246:247], v[246:247], 0, v[244:245]
	v_mov_b32_e32 v2, 0
	v_mov_b32_e32 v3, 0
	v_mov_b32_e32 v4, 0
	v_mov_b32_e32 v5, 0
	v_mov_b32_e32 v6, 0
	v_mov_b32_e32 v7, 0
	v_mov_b32_e32 v8, 0
	v_mov_b32_e32 v9, 0
	v_mov_b32_e32 v10, 0
	v_mov_b32_e32 v11, 0
	v_mov_b32_e32 v12, 0
	v_mov_b32_e32 v13, 0
	v_mov_b32_e32 v14, 0
	v_mov_b32_e32 v15, 0
	v_mov_b32_e32 v16, 0
	v_mov_b32_e32 v17, 0
	v_mov_b32_e32 v18, 0
	v_mov_b32_e32 v19, 0
	v_mov_b32_e32 v20, 0
	v_mov_b32_e32 v21, 0
	v_mov_b32_e32 v22, 0
	v_mov_b32_e32 v23, 0
	v_mov_b32_e32 v24, 0
	v_mov_b32_e32 v25, 0
	v_mov_b32_e32 v26, 0
	v_mov_b32_e32 v27, 0
	v_mov_b32_e32 v28, 0
	v_mov_b32_e32 v29, 0
	v_mov_b32_e32 v30, 0
	v_mov_b32_e32 v31, 0
	v_mov_b32_e32 v32, 0
	v_mov_b32_e32 v33, 0
	v_mov_b32_e32 v34, 0
	v_mov_b32_e32 v35, 0
	v_mov_b32_e32 v36, 0
	v_mov_b32_e32 v37, 0
	v_mov_b32_e32 v38, 0
	v_mov_b32_e32 v39, 0
	v_mov_b32_e32 v40, 0
	v_mov_b32_e32 v41, 0
	v_mov_b32_e32 v42, 0
	v_mov_b32_e32 v43, 0
	v_mov_b32_e32 v44, 0
	v_mov_b32_e32 v45, 0
	v_mov_b32_e32 v46, 0
	v_mov_b32_e32 v47, 0
	v_mov_b32_e32 v48, 0
	v_mov_b32_e32 v49, 0
	v_mov_b32_e32 v50, 0
	v_mov_b32_e32 v51, 0
	v_mov_b32_e32 v52, 0
	v_mov_b32_e32 v53, 0
	v_mov_b32_e32 v54, 0
	v_mov_b32_e32 v55, 0
	v_mov_b32_e32 v56, 0
	v_mov_b32_e32 v57, 0
	v_mov_b32_e32 v58, 0
	v_mov_b32_e32 v59, 0
	v_mov_b32_e32 v60, 0
	v_mov_b32_e32 v61, 0
	v_mov_b32_e32 v62, 0
	v_mov_b32_e32 v63, 0
	v_mov_b32_e32 v64, 0
	v_mov_b32_e32 v65, 0
	v_mov_b32_e32 v238, 0
	v_add_u32_e32 v245, 0xffffff00, v235
	s_sub_i32 s65, s78, 0x80
	s_mov_b32 s40, 0
	s_waitcnt vmcnt(0) lgkmcnt(0)
	s_barrier
	s_mov_b32 s24, 0
	s_lshl_b32 s12, s24, 13
	s_add_i32 s12, s12, s66
	s_lshl_b32 s13, s24, 14
	s_add_i32 s13, s13, s74
	s_add_i32 m0, s12, 0x14000
	s_nop 0
	global_load_lds_dwordx4 v[184:185], off
	s_mov_b32 m0, s13
	v_lshl_add_u64 v[184:185], v[184:185], 0, s[6:7]
	global_load_lds_dwordx4 v[250:251], off
	s_add_i32 m0, s13, 0x400
	v_lshl_add_u64 v[250:251], v[250:251], 0, s[6:7]
	global_load_lds_dwordx4 v[246:247], off
	v_lshl_add_u64 v[246:247], v[246:247], 0, s[6:7]
	s_mov_b32 s24, 1
	s_lshl_b32 s12, s24, 13
	s_add_i32 s12, s12, s66
	s_lshl_b32 s13, s24, 14
	s_add_i32 s13, s13, s74
	s_add_i32 m0, s12, 0x14000
	s_nop 0
	global_load_lds_dwordx4 v[184:185], off
	s_mov_b32 m0, s13
	v_lshl_add_u64 v[184:185], v[184:185], 0, s[6:7]
	global_load_lds_dwordx4 v[250:251], off
	s_add_i32 m0, s13, 0x400
	v_lshl_add_u64 v[250:251], v[250:251], 0, s[6:7]
	global_load_lds_dwordx4 v[246:247], off
	v_lshl_add_u64 v[246:247], v[246:247], 0, s[6:7]
	s_waitcnt vmcnt(3)
	s_barrier
	s_cmp_eq_u32 s67, 0
	s_cbranch_scc1 .Lat_enter
	s_barrier
.Lat_enter:
	s_add_i32 s24, s40, 2
	s_and_b32 s24, s24, 3
	s_lshl_b32 s12, s24, 13
	s_add_i32 s12, s12, s66
	s_lshl_b32 s13, s24, 14
	s_add_i32 s13, s13, s74
	s_add_i32 m0, s12, 0x14000
	s_nop 0
	global_load_lds_dwordx4 v[184:185], off
	s_mov_b32 m0, s13
	v_lshl_add_u64 v[184:185], v[184:185], 0, s[6:7]
	global_load_lds_dwordx4 v[250:251], off
	s_add_i32 m0, s13, 0x400
	v_lshl_add_u64 v[250:251], v[250:251], 0, s[6:7]
	global_load_lds_dwordx4 v[246:247], off
	v_lshl_add_u64 v[246:247], v[246:247], 0, s[6:7]
	s_and_b32 s41, s40, 3
	s_lshl_b32 s41, s41, 13
	v_add_u32_e32 v244, s41, v239
	v_add_u32_e32 v249, s41, v240
	v_add_u32_e32 v220, s41, v241
	v_add_u32_e32 v248, s41, v242
	ds_read_b128 v[98:101], v244
	ds_read_b128 v[102:105], v244 offset:4096
	ds_read_b128 v[106:109], v249
	ds_read_b128 v[110:113], v249 offset:4096
	ds_read_b128 v[114:117], v220
	ds_read_b128 v[118:121], v220 offset:4096
	ds_read_b128 v[122:125], v248
	ds_read_b128 v[126:129], v248 offset:4096
	s_add_i32 s12, s65, 190
	s_cmp_lt_u32 s12, 349
	s_cbranch_scc1 .Lat_near_p
	s_cmp_lt_i32 s65, 0
	s_cselect_b64 vcc, -1, 0
	v_cndmask_b32_e32 v0, v224, v223, vcc
	s_waitcnt lgkmcnt(0)
	v_mfma_f32_32x32x16_bf16 v[82:97], v[98:101], v[142:145], 0
	v_mfma_f32_32x32x16_bf16 v[66:81], v[102:105], v[142:145], 0
	v_mfma_f32_32x32x16_bf16 v[82:97], v[106:109], v[138:141], v[82:97]
	v_mfma_f32_32x32x16_bf16 v[66:81], v[110:113], v[138:141], v[66:81]
	v_mfma_f32_32x32x16_bf16 v[82:97], v[114:117], v[134:137], v[82:97]
	v_mfma_f32_32x32x16_bf16 v[66:81], v[118:121], v[134:137], v[66:81]
	v_mfma_f32_32x32x16_bf16 v[82:97], v[122:125], v[130:133], v[82:97]
	v_mfma_f32_32x32x16_bf16 v[66:81], v[126:129], v[130:133], v[66:81]
	s_branch .Lat_qkd_p

; #define MX3(a, b, c) __builtin_fmaxf(__builtin_fmaxf((a), (b)), (c))
; __device__ __forceinline__ void partialSM(f32x16& p0, f32x16& p1, float& m_reg, float& mn, float& alpha, float boff) {
;     constexpr float C = SCALE * 1.4426950408889634f;
;     float a = MX3(p0[0], p0[1], p1[0]), b = MX3(p0[2], p0[3], p1[1]); a = MX3(a, p1[2], p1[3]);
; #pragma unroll
;     for (int r = 4; r < 16; r += 4) { a = MX3(a, p0[r], p0[r + 1]); b = MX3(b, p0[r + 2], p0[r + 3]); a = MX3(a, p1[r], p1[r + 1]); b = MX3(b, p1[r + 2], p1[r + 3]); }
;     float pmax = __builtin_fmaxf(a, b);
;     { auto rr = __builtin_amdgcn_permlane32_swap(__float_as_uint(pmax), __float_as_uint(pmax), false, false);
;       pmax = fmaxf(__uint_as_float(rr[0]), __uint_as_float(rr[1])) + boff; }
;     if (__builtin_expect(__all(pmax - m_reg <= THR / SCALE), 1)) { mn = m_reg; alpha = 1.f; }
;     else { mn = fmaxf(m_reg, pmax); alpha = __builtin_amdgcn_exp2f((m_reg - mn) * C); m_reg = mn; }
.Lat_qkd_p:
	s_nop 15
	s_waitcnt vmcnt(3)
	s_barrier
	v_max_f32_e32 v244, v82, v83
	v_max3_f32 v249, v84, v85, v67
	v_max3_f32 v244, v244, v66, v68
	v_max3_f32 v244, v244, v69, v86
	v_max3_f32 v249, v249, v88, v89
	v_max3_f32 v244, v244, v87, v70
	v_max3_f32 v249, v249, v72, v73
	v_max3_f32 v244, v244, v71, v90
	v_max3_f32 v249, v249, v92, v93
	v_max3_f32 v244, v244, v91, v74
	v_max3_f32 v249, v249, v76, v77
	v_max3_f32 v244, v244, v75, v94
	v_max3_f32 v249, v249, v96, v97
	v_max3_f32 v244, v244, v95, v78
	v_max3_f32 v249, v249, v80, v81
	v_max3_f32 v244, v244, v79, v249
	v_mov_b32_e32 v249, v244
	s_nop 1
	v_permlane32_swap_b32_e32 v244, v249
	v_max_f32_e32 v244, v244, v249
	v_add_f32_e32 v244, v0, v244
	v_sub_f32_e32 v249, v244, v243
	v_cmp_ge_f32_e32 vcc, s72, v249
	v_max_f32_e32 v249, v243, v244
	v_sub_f32_e32 v220, v243, v249
	v_mul_f32_e32 v220, 0x3e38aa3b, v220
	v_exp_f32_e32 v220, v220
	s_cmp_eq_u64 vcc, exec
	s_cselect_b64 s[0:1], -1, 0
	v_cndmask_b32_e64 v248, v220, 1.0, s[0:1]
	v_cmp_gt_f32_e32 vcc, 1.0, v248
	s_cbranch_vccz .Lat_noresc_p
	s_and_saveexec_b64 s[12:13], s[38:39]
	ds_write_b32 v232, v248 offset:128
	s_or_b64 exec, exec, s[12:13]
	s_waitcnt lgkmcnt(0)
	v_add_u32_e32 v110, s31, v188
	ds_read_b128 v[98:101], v110 offset:224
	ds_read_b128 v[102:105], v110 offset:192
	ds_read_b128 v[106:109], v110 offset:160
	ds_read_b128 v[110:113], v110 offset:128
	s_waitcnt lgkmcnt(0)
	v_pk_mul_f32 v[62:63], v[62:63], v[98:99]
	v_pk_mul_f32 v[58:59], v[58:59], v[102:103]
	v_pk_mul_f32 v[54:55], v[54:55], v[106:107]
	v_pk_mul_f32 v[64:65], v[64:65], v[100:101]
	v_pk_mul_f32 v[60:61], v[60:61], v[104:105]
	v_pk_mul_f32 v[56:57], v[56:57], v[108:109]
	v_pk_mul_f32 v[52:53], v[52:53], v[112:113]
	v_pk_mul_f32 v[50:51], v[50:51], v[110:111]
	v_pk_mul_f32 v[46:47], v[46:47], v[98:99]
	v_pk_mul_f32 v[42:43], v[42:43], v[102:103]
	v_pk_mul_f32 v[38:39], v[38:39], v[106:107]
	v_pk_mul_f32 v[48:49], v[48:49], v[100:101]
	v_pk_mul_f32 v[44:45], v[44:45], v[104:105]
	v_pk_mul_f32 v[40:41], v[40:41], v[108:109]
	v_pk_mul_f32 v[36:37], v[36:37], v[112:113]
	v_pk_mul_f32 v[34:35], v[34:35], v[110:111]
	v_pk_mul_f32 v[30:31], v[30:31], v[98:99]
	v_pk_mul_f32 v[26:27], v[26:27], v[102:103]
	v_pk_mul_f32 v[22:23], v[22:23], v[106:107]
	v_pk_mul_f32 v[32:33], v[32:33], v[100:101]
	v_pk_mul_f32 v[28:29], v[28:29], v[104:105]
	v_pk_mul_f32 v[24:25], v[24:25], v[108:109]
	v_pk_mul_f32 v[20:21], v[20:21], v[112:113]
	v_pk_mul_f32 v[18:19], v[18:19], v[110:111]
	v_pk_mul_f32 v[14:15], v[14:15], v[98:99]
	v_pk_mul_f32 v[10:11], v[10:11], v[102:103]
	v_pk_mul_f32 v[6:7], v[6:7], v[106:107]
	v_pk_mul_f32 v[16:17], v[16:17], v[100:101]
	v_pk_mul_f32 v[12:13], v[12:13], v[104:105]
	v_pk_mul_f32 v[8:9], v[8:9], v[108:109]
	v_pk_mul_f32 v[4:5], v[4:5], v[112:113]
	v_pk_mul_f32 v[2:3], v[2:3], v[110:111]
; #define SBAR() __builtin_amdgcn_sched_barrier(0)
; #define WAITBAR(N) asm volatile("s_waitcnt vmcnt(" #N ") lgkmcnt(0)\n\ts_barrier" ::: "memory")
; #define ROT() do { const int t_ = bp; bp = bc; bc = bn; bn = t_; } while (0)
; __device__ __forceinline__ void partialSM(f32x16& p0, f32x16& p1, float& m_reg, float& mn, float& alpha, float boff) {
;     ...
;     const float mnC = (boff - mn) * C;
; #pragma unroll
;     for (int r = 0; r < 16; ++r) p0[r] = fmaf(p0[r], C, mnC);
; #pragma unroll
;     for (int r = 0; r < 16; ++r) p1[r] = fmaf(p1[r], C, mnC);
; #pragma unroll
;     for (int r = 0; r < 16; ++r) p0[r] = __builtin_amdgcn_exp2f(p0[r]);
; }
; __device__ __forceinline__ void finishSM(f32x16& p0, f32x16& p1, float alpha, float& l_reg, bf16x8& pa0, bf16x8& pa1, bf16x8& pa2, bf16x8& pa3) {
; #pragma unroll
;     for (int r = 0; r < 16; ++r) p1[r] = __builtin_amdgcn_exp2f(p1[r]);
;     float ps = 0;
; #pragma unroll
;     for (int r = 0; r < 16; ++r) ps += p0[r];
; #pragma unroll
;     for (int r = 0; r < 16; ++r) ps += p1[r];
;     { auto rr = __builtin_amdgcn_permlane32_swap(__float_as_uint(ps), __float_as_uint(ps), false, false);
;       ps = __uint_as_float(rr[0]) + __uint_as_float(rr[1]); }
;     l_reg = l_reg * alpha + ps;
;     ...
;     PK4(p0, 0, pa0); PK4(p0, 8, pa1); PK4(p1, 0, pa2); PK4(p1, 8, pa3);
; __device__ __forceinline__ void attn_unit(int b, int h, int qb, const bf16_t* __restrict__ proj, const float* __restrict__ btab, float lam, float outscale,
;                                           const float* __restrict__ gain, float* o1scr, bf16_t* merged, LAS char* lds) {
;     ...
;         for (int j = 1; j + 1 < NT; j += 2) {
;             WAITBAR(0);
;             DMA_TILE(j + 1, bn);
;             SBAR(); bo = qkt(pB0, pB1, K_lds + bc * SHM_K, qr, r32, hi, j * 64 - qw, cL, cR, tabL);
;             finishSM(pA0, pA1, alA, l_reg, pa0, pa1, pa2, pa3); SBAR();
;             pv_d0(o, vb0 + bp * SHM_V, pa0, pa1, pa2, pa3); partialSM(pB0, pB1, m_reg, mnB, alB, bo);
;             RESC(alB); ROT();
;             WAITBAR(0);
;             if (j + 2 < NT) DMA_TILE(j + 2, bn);
;             SBAR(); bo = qkt(pA0, pA1, K_lds + bc * SHM_K, qr, r32, hi, (j + 1) * 64 - qw, cL, cR, tabL);
.Lat_noresc_p:
	v_cndmask_b32_e64 v243, v249, v243, s[0:1]
	v_sub_f32_e32 v0, v0, v243
	v_mul_f32_e32 v0, 0x3e38aa3b, v0
	v_fmamk_f32 v82, v82, 0x3e38aa3b, v0
	v_fmamk_f32 v83, v83, 0x3e38aa3b, v0
	v_fmamk_f32 v84, v84, 0x3e38aa3b, v0
	v_fmamk_f32 v85, v85, 0x3e38aa3b, v0
	v_fmamk_f32 v86, v86, 0x3e38aa3b, v0
	v_fmamk_f32 v87, v87, 0x3e38aa3b, v0
	v_fmamk_f32 v88, v88, 0x3e38aa3b, v0
	v_fmamk_f32 v89, v89, 0x3e38aa3b, v0
	v_fmamk_f32 v90, v90, 0x3e38aa3b, v0
	v_fmamk_f32 v91, v91, 0x3e38aa3b, v0
	v_fmamk_f32 v92, v92, 0x3e38aa3b, v0
	v_fmamk_f32 v93, v93, 0x3e38aa3b, v0
	v_fmamk_f32 v94, v94, 0x3e38aa3b, v0
	v_fmamk_f32 v95, v95, 0x3e38aa3b, v0
	v_fmamk_f32 v96, v96, 0x3e38aa3b, v0
	v_fmamk_f32 v97, v97, 0x3e38aa3b, v0
	v_fmamk_f32 v66, v66, 0x3e38aa3b, v0
	v_fmamk_f32 v67, v67, 0x3e38aa3b, v0
	v_fmamk_f32 v68, v68, 0x3e38aa3b, v0
	v_fmamk_f32 v69, v69, 0x3e38aa3b, v0
	v_fmamk_f32 v70, v70, 0x3e38aa3b, v0
	v_fmamk_f32 v71, v71, 0x3e38aa3b, v0
	v_fmamk_f32 v72, v72, 0x3e38aa3b, v0
	v_fmamk_f32 v73, v73, 0x3e38aa3b, v0
	v_fmamk_f32 v74, v74, 0x3e38aa3b, v0
	v_fmamk_f32 v75, v75, 0x3e38aa3b, v0
	v_fmamk_f32 v76, v76, 0x3e38aa3b, v0
	v_fmamk_f32 v77, v77, 0x3e38aa3b, v0
	v_fmamk_f32 v78, v78, 0x3e38aa3b, v0
	v_fmamk_f32 v79, v79, 0x3e38aa3b, v0
	v_fmamk_f32 v80, v80, 0x3e38aa3b, v0
	v_fmamk_f32 v81, v81, 0x3e38aa3b, v0
	v_exp_f32_e32 v82, v82
	v_exp_f32_e32 v83, v83
	v_exp_f32_e32 v84, v84
	v_exp_f32_e32 v85, v85
	v_exp_f32_e32 v86, v86
	v_exp_f32_e32 v87, v87
	v_exp_f32_e32 v88, v88
	v_exp_f32_e32 v89, v89
	v_exp_f32_e32 v90, v90
	v_exp_f32_e32 v91, v91
	v_exp_f32_e32 v92, v92
	v_exp_f32_e32 v93, v93
	v_exp_f32_e32 v94, v94
	v_exp_f32_e32 v95, v95
	v_exp_f32_e32 v96, v96
	v_exp_f32_e32 v97, v97
	v_exp_f32_e32 v66, v66
	v_add_f32_e32 v244, v82, v83
	v_exp_f32_e32 v67, v67
	v_add_f32_e32 v244, v84, v244
	v_exp_f32_e32 v68, v68
	v_add_f32_e32 v244, v85, v244
	v_exp_f32_e32 v69, v69
	v_add_f32_e32 v244, v86, v244
	v_exp_f32_e32 v70, v70
	v_add_f32_e32 v244, v87, v244
	v_exp_f32_e32 v71, v71
	v_add_f32_e32 v244, v88, v244
	v_exp_f32_e32 v72, v72
	v_add_f32_e32 v244, v89, v244
	v_exp_f32_e32 v73, v73
	v_add_f32_e32 v244, v90, v244
	v_exp_f32_e32 v74, v74
	v_add_f32_e32 v244, v91, v244
	v_exp_f32_e32 v75, v75
	v_add_f32_e32 v244, v92, v244
	v_exp_f32_e32 v76, v76
	v_add_f32_e32 v244, v93, v244
	v_exp_f32_e32 v77, v77
	v_add_f32_e32 v244, v94, v244
	v_exp_f32_e32 v78, v78
	v_add_f32_e32 v244, v95, v244
	v_exp_f32_e32 v79, v79
	v_add_f32_e32 v244, v96, v244
	v_exp_f32_e32 v80, v80
	v_add_f32_e32 v244, v97, v244
	v_exp_f32_e32 v81, v81
	v_add_f32_e32 v249, v66, v67
	v_add_f32_e32 v249, v68, v249
	v_add_f32_e32 v249, v69, v249
	v_add_f32_e32 v249, v70, v249
	v_add_f32_e32 v249, v71, v249
	v_add_f32_e32 v249, v72, v249
	v_add_f32_e32 v249, v73, v249
	v_add_f32_e32 v249, v74, v249
	v_add_f32_e32 v249, v75, v249
	v_add_f32_e32 v249, v76, v249
	v_add_f32_e32 v249, v77, v249
	v_add_f32_e32 v249, v78, v249
	v_add_f32_e32 v249, v79, v249
	v_add_f32_e32 v249, v80, v249
	v_add_f32_e32 v249, v81, v249
	v_add_f32_e32 v244, v244, v249
	v_fma_f32 v238, v238, v248, v244
	v_cvt_pk_bf16_f32 v146, v82, v83
	v_cvt_pk_bf16_f32 v147, v84, v85
	v_cvt_pk_bf16_f32 v148, v86, v87
	v_cvt_pk_bf16_f32 v149, v88, v89
	v_cvt_pk_bf16_f32 v150, v90, v91
	v_cvt_pk_bf16_f32 v151, v92, v93
	v_cvt_pk_bf16_f32 v152, v94, v95
	v_cvt_pk_bf16_f32 v153, v96, v97
	v_cvt_pk_bf16_f32 v154, v66, v67
	v_cvt_pk_bf16_f32 v155, v68, v69
	v_cvt_pk_bf16_f32 v156, v70, v71
	v_cvt_pk_bf16_f32 v157, v72, v73
	v_cvt_pk_bf16_f32 v158, v74, v75
	v_cvt_pk_bf16_f32 v159, v76, v77
	v_cvt_pk_bf16_f32 v160, v78, v79
	v_cvt_pk_bf16_f32 v161, v80, v81
	s_add_i32 s40, s40, 1
	s_addk_i32 s65, 0x40
	v_add_u32_e32 v245, 0x100, v245
	s_barrier
.Lat_loop:
	s_cmp_gt_u32 s40, 61
	s_cbranch_scc1 .Lat_nodma_l
	s_add_i32 s24, s40, 2
	s_and_b32 s24, s24, 3
	s_lshl_b32 s12, s24, 13
	s_add_i32 s12, s12, s66
	s_lshl_b32 s13, s24, 14
	s_add_i32 s13, s13, s74
	s_add_i32 m0, s12, 0x14000
	s_nop 0
	global_load_lds_dwordx4 v[184:185], off
	s_mov_b32 m0, s13
	v_lshl_add_u64 v[184:185], v[184:185], 0, s[6:7]
	global_load_lds_dwordx4 v[250:251], off
	s_add_i32 m0, s13, 0x400
	v_lshl_add_u64 v[250:251], v[250:251], 0, s[6:7]
	global_load_lds_dwordx4 v[246:247], off
	v_lshl_add_u64 v[246:247], v[246:247], 0, s[6:7]
.Lat_nodma_l:
	s_and_b32 s41, s40, 3
	s_lshl_b32 s41, s41, 13
	v_add_u32_e32 v244, s41, v239
	v_add_u32_e32 v249, s41, v240
	v_add_u32_e32 v220, s41, v241
	v_add_u32_e32 v248, s41, v242
	ds_read_b128 v[98:101], v244
	ds_read_b128 v[102:105], v244 offset:4096
	ds_read_b128 v[106:109], v249
	ds_read_b128 v[110:113], v249 offset:4096
	ds_read_b128 v[114:117], v220
	ds_read_b128 v[118:121], v220 offset:4096
	ds_read_b128 v[122:125], v248
	ds_read_b128 v[126:129], v248 offset:4096
	s_add_i32 s12, s65, 190
	s_cmp_lt_u32 s12, 349
	s_cbranch_scc1 .Lat_near_l
	s_cmp_lt_i32 s65, 0
	s_cselect_b64 vcc, -1, 0
	v_cndmask_b32_e32 v0, v224, v223, vcc
	s_add_i32 s54, s40, 3
	s_and_b32 s54, s54, 3
	s_lshl_b32 s54, s54, 14
	v_add_u32_e32 v244, s54, v225
	ds_read_b64_tr_b16 v[162:163], v244 offset:0x0
	ds_read_b64_tr_b16 v[164:165], v244 offset:0x800
	ds_read_b64_tr_b16 v[166:167], v244 offset:0x1000
	ds_read_b64_tr_b16 v[168:169], v244 offset:0x1800
	ds_read_b64_tr_b16 v[170:171], v244 offset:0x2000
	ds_read_b64_tr_b16 v[172:173], v244 offset:0x2800
	ds_read_b64_tr_b16 v[174:175], v244 offset:0x3000
	ds_read_b64_tr_b16 v[176:177], v244 offset:0x3800
	s_waitcnt lgkmcnt(8)
	v_mfma_f32_32x32x16_bf16 v[82:97], v[98:101], v[142:145], 0
	v_mfma_f32_32x32x16_bf16 v[66:81], v[102:105], v[142:145], 0
	v_mfma_f32_32x32x16_bf16 v[82:97], v[106:109], v[138:141], v[82:97]
	v_mfma_f32_32x32x16_bf16 v[66:81], v[110:113], v[138:141], v[66:81]
	v_mfma_f32_32x32x16_bf16 v[82:97], v[114:117], v[134:137], v[82:97]
	v_mfma_f32_32x32x16_bf16 v[66:81], v[118:121], v[134:137], v[66:81]
	v_mfma_f32_32x32x16_bf16 v[82:97], v[122:125], v[130:133], v[82:97]
	v_mfma_f32_32x32x16_bf16 v[66:81], v[126:129], v[130:133], v[66:81]
	s_branch .Lat_qkd_l

; #define MX3(a, b, c) __builtin_fmaxf(__builtin_fmaxf((a), (b)), (c))
; __device__ __forceinline__ void partialSM(f32x16& p0, f32x16& p1, float& m_reg, float& mn, float& alpha, float boff) {
;     constexpr float C = SCALE * 1.4426950408889634f;
;     float a = MX3(p0[0], p0[1], p1[0]), b = MX3(p0[2], p0[3], p1[1]); a = MX3(a, p1[2], p1[3]);
; #pragma unroll
;     for (int r = 4; r < 16; r += 4) { a = MX3(a, p0[r], p0[r + 1]); b = MX3(b, p0[r + 2], p0[r + 3]); a = MX3(a, p1[r], p1[r + 1]); b = MX3(b, p1[r + 2], p1[r + 3]); }
;     float pmax = __builtin_fmaxf(a, b);
;     { auto rr = __builtin_amdgcn_permlane32_swap(__float_as_uint(pmax), __float_as_uint(pmax), false, false);
;       pmax = fmaxf(__uint_as_float(rr[0]), __uint_as_float(rr[1])) + boff; }
;     if (__builtin_expect(__all(pmax - m_reg <= THR / SCALE), 1)) { mn = m_reg; alpha = 1.f; }
;     else { mn = fmaxf(m_reg, pmax); alpha = __builtin_amdgcn_exp2f((m_reg - mn) * C); m_reg = mn; }
.Lat_wd_l:
	s_barrier
	v_max_f32_e32 v244, v82, v83
	v_max3_f32 v249, v84, v85, v67
	v_max3_f32 v244, v244, v66, v68
	v_max3_f32 v244, v244, v69, v86
	v_max3_f32 v249, v249, v88, v89
	v_max3_f32 v244, v244, v87, v70
	v_max3_f32 v249, v249, v72, v73
	v_max3_f32 v244, v244, v71, v90
	v_max3_f32 v249, v249, v92, v93
	v_max3_f32 v244, v244, v91, v74
	v_max3_f32 v249, v249, v76, v77
	v_max3_f32 v244, v244, v75, v94
	v_max3_f32 v249, v249, v96, v97
	v_max3_f32 v244, v244, v95, v78
	v_max3_f32 v249, v249, v80, v81
	v_max3_f32 v244, v244, v79, v249
	v_mov_b32_e32 v249, v244
	s_nop 1
	v_permlane32_swap_b32_e32 v244, v249
	v_max_f32_e32 v244, v244, v249
	v_add_f32_e32 v244, v0, v244
	v_sub_f32_e32 v249, v244, v243
	v_cmp_ge_f32_e32 vcc, s72, v249
	v_max_f32_e32 v249, v243, v244
	v_sub_f32_e32 v220, v243, v249
	v_mul_f32_e32 v220, 0x3e38aa3b, v220
	v_exp_f32_e32 v220, v220
	s_cmp_eq_u64 vcc, exec
	s_cselect_b64 s[0:1], -1, 0
	v_cndmask_b32_e64 v248, v220, 1.0, s[0:1]
	v_cmp_gt_f32_e32 vcc, 1.0, v248
	s_cbranch_vccz .Lat_noresc_l
	s_and_saveexec_b64 s[12:13], s[38:39]
	ds_write_b32 v232, v248 offset:128
	s_or_b64 exec, exec, s[12:13]
	s_waitcnt lgkmcnt(0)
	v_add_u32_e32 v110, s31, v188
	ds_read_b128 v[98:101], v110 offset:224
	ds_read_b128 v[102:105], v110 offset:192
	ds_read_b128 v[106:109], v110 offset:160
	ds_read_b128 v[110:113], v110 offset:128
	s_waitcnt lgkmcnt(0)
	v_pk_mul_f32 v[62:63], v[62:63], v[98:99]
	v_pk_mul_f32 v[58:59], v[58:59], v[102:103]
	v_pk_mul_f32 v[54:55], v[54:55], v[106:107]
	v_pk_mul_f32 v[64:65], v[64:65], v[100:101]
	v_pk_mul_f32 v[60:61], v[60:61], v[104:105]
	v_pk_mul_f32 v[56:57], v[56:57], v[108:109]
	v_pk_mul_f32 v[52:53], v[52:53], v[112:113]
	v_pk_mul_f32 v[50:51], v[50:51], v[110:111]
	v_pk_mul_f32 v[46:47], v[46:47], v[98:99]
	v_pk_mul_f32 v[42:43], v[42:43], v[102:103]
	v_pk_mul_f32 v[38:39], v[38:39], v[106:107]
	v_pk_mul_f32 v[48:49], v[48:49], v[100:101]
	v_pk_mul_f32 v[44:45], v[44:45], v[104:105]
	v_pk_mul_f32 v[40:41], v[40:41], v[108:109]
	v_pk_mul_f32 v[36:37], v[36:37], v[112:113]
	v_pk_mul_f32 v[34:35], v[34:35], v[110:111]
	v_pk_mul_f32 v[30:31], v[30:31], v[98:99]
	v_pk_mul_f32 v[26:27], v[26:27], v[102:103]
	v_pk_mul_f32 v[22:23], v[22:23], v[106:107]
	v_pk_mul_f32 v[32:33], v[32:33], v[100:101]
	v_pk_mul_f32 v[28:29], v[28:29], v[104:105]
	v_pk_mul_f32 v[24:25], v[24:25], v[108:109]
	v_pk_mul_f32 v[20:21], v[20:21], v[112:113]
	v_pk_mul_f32 v[18:19], v[18:19], v[110:111]
	v_pk_mul_f32 v[14:15], v[14:15], v[98:99]
	v_pk_mul_f32 v[10:11], v[10:11], v[102:103]
	v_pk_mul_f32 v[6:7], v[6:7], v[106:107]
	v_pk_mul_f32 v[16:17], v[16:17], v[100:101]
	v_pk_mul_f32 v[12:13], v[12:13], v[104:105]
	v_pk_mul_f32 v[8:9], v[8:9], v[108:109]
	v_pk_mul_f32 v[4:5], v[4:5], v[112:113]
	v_pk_mul_f32 v[2:3], v[2:3], v[110:111]
; #define SBAR() __builtin_amdgcn_sched_barrier(0)
; __device__ __forceinline__ void partialSM(f32x16& p0, f32x16& p1, float& m_reg, float& mn, float& alpha, float boff) {
;     ...
;     const float mnC = (boff - mn) * C;
; #pragma unroll
;     for (int r = 0; r < 16; ++r) p0[r] = fmaf(p0[r], C, mnC);
; #pragma unroll
;     for (int r = 0; r < 16; ++r) p1[r] = fmaf(p1[r], C, mnC);
; #pragma unroll
;     for (int r = 0; r < 16; ++r) p0[r] = __builtin_amdgcn_exp2f(p0[r]);
; }
; __device__ __forceinline__ void finishSM(f32x16& p0, f32x16& p1, float alpha, float& l_reg, bf16x8& pa0, bf16x8& pa1, bf16x8& pa2, bf16x8& pa3) {
; #pragma unroll
;     for (int r = 0; r < 16; ++r) p1[r] = __builtin_amdgcn_exp2f(p1[r]);
;     float ps = 0;
; #pragma unroll
;     for (int r = 0; r < 16; ++r) ps += p0[r];
; #pragma unroll
;     for (int r = 0; r < 16; ++r) ps += p1[r];
;     { auto rr = __builtin_amdgcn_permlane32_swap(__float_as_uint(ps), __float_as_uint(ps), false, false);
;       ps = __uint_as_float(rr[0]) + __uint_as_float(rr[1]); }
;     l_reg = l_reg * alpha + ps;
;     ...
;     PK4(p0, 0, pa0); PK4(p0, 8, pa1); PK4(p1, 0, pa2); PK4(p1, 8, pa3);
; template <int D0> __device__ __forceinline__ void pv_one(f32x16& od, int vb, bf16x8 pa0, bf16x8 pa1, bf16x8 pa2, bf16x8 pa3) {
;     const s16x4 l0 = tr_read<v_rd_off(D0, 0, 0)>(vb), h0 = tr_read<v_rd_off(D0, 0, 1)>(vb), l1 = tr_read<v_rd_off(D0, 1, 0)>(vb), h1 = tr_read<v_rd_off(D0, 1, 1)>(vb);
;     const s16x4 l2 = tr_read<v_rd_off(D0, 2, 0)>(vb), h2 = tr_read<v_rd_off(D0, 2, 1)>(vb), l3 = tr_read<v_rd_off(D0, 3, 0)>(vb), h3 = tr_read<v_rd_off(D0, 3, 1)>(vb);
;     asm volatile("s_waitcnt lgkmcnt(0)" ::: "memory"); SBAR();
;     ...
;     od = __builtin_amdgcn_mfma_f32_32x32x16_bf16(pa0, PK(l0, h0), od, 0, 0, 0);
;     od = __builtin_amdgcn_mfma_f32_32x32x16_bf16(pa1, PK(l1, h1), od, 0, 0, 0);
;     od = __builtin_amdgcn_mfma_f32_32x32x16_bf16(pa2, PK(l2, h2), od, 0, 0, 0);
;     od = __builtin_amdgcn_mfma_f32_32x32x16_bf16(pa3, PK(l3, h3), od, 0, 0, 0);
;     ...
; }
; __device__ __forceinline__ void pv_d0(f32x16* o, int vb, bf16x8 pa0, bf16x8 pa1, bf16x8 pa2, bf16x8 pa3) {
;     pv_one<0>(o[0], vb, pa0, pa1, pa2, pa3); pv_one<1>(o[1], vb, pa0, pa1, pa2, pa3); pv_one<2>(o[2], vb, pa0, pa1, pa2, pa3); pv_one<3>(o[3], vb, pa0, pa1, pa2, pa3);
.Lat_noresc_l:
	v_cndmask_b32_e64 v243, v249, v243, s[0:1]
	v_sub_f32_e32 v0, v0, v243
	v_mul_f32_e32 v0, 0x3e38aa3b, v0
	v_fmamk_f32 v82, v82, 0x3e38aa3b, v0
	v_fmamk_f32 v83, v83, 0x3e38aa3b, v0
	v_fmamk_f32 v84, v84, 0x3e38aa3b, v0
	v_fmamk_f32 v85, v85, 0x3e38aa3b, v0
	v_fmamk_f32 v86, v86, 0x3e38aa3b, v0
	v_fmamk_f32 v87, v87, 0x3e38aa3b, v0
	v_fmamk_f32 v88, v88, 0x3e38aa3b, v0
	v_fmamk_f32 v89, v89, 0x3e38aa3b, v0
	v_fmamk_f32 v90, v90, 0x3e38aa3b, v0
	v_fmamk_f32 v91, v91, 0x3e38aa3b, v0
	v_fmamk_f32 v92, v92, 0x3e38aa3b, v0
	v_fmamk_f32 v93, v93, 0x3e38aa3b, v0
	v_fmamk_f32 v94, v94, 0x3e38aa3b, v0
	v_fmamk_f32 v95, v95, 0x3e38aa3b, v0
	v_fmamk_f32 v96, v96, 0x3e38aa3b, v0
	v_fmamk_f32 v97, v97, 0x3e38aa3b, v0
	v_fmamk_f32 v66, v66, 0x3e38aa3b, v0
	v_fmamk_f32 v67, v67, 0x3e38aa3b, v0
	v_fmamk_f32 v68, v68, 0x3e38aa3b, v0
	v_fmamk_f32 v69, v69, 0x3e38aa3b, v0
	v_fmamk_f32 v70, v70, 0x3e38aa3b, v0
	v_fmamk_f32 v71, v71, 0x3e38aa3b, v0
	v_fmamk_f32 v72, v72, 0x3e38aa3b, v0
	v_fmamk_f32 v73, v73, 0x3e38aa3b, v0
	v_fmamk_f32 v74, v74, 0x3e38aa3b, v0
	v_fmamk_f32 v75, v75, 0x3e38aa3b, v0
	v_fmamk_f32 v76, v76, 0x3e38aa3b, v0
	v_fmamk_f32 v77, v77, 0x3e38aa3b, v0
	v_fmamk_f32 v78, v78, 0x3e38aa3b, v0
	v_fmamk_f32 v79, v79, 0x3e38aa3b, v0
	v_fmamk_f32 v80, v80, 0x3e38aa3b, v0
	v_fmamk_f32 v81, v81, 0x3e38aa3b, v0
	v_exp_f32_e32 v82, v82
	v_exp_f32_e32 v83, v83
	v_exp_f32_e32 v84, v84
	v_exp_f32_e32 v85, v85
	v_exp_f32_e32 v86, v86
	v_exp_f32_e32 v87, v87
	v_exp_f32_e32 v88, v88
	v_exp_f32_e32 v89, v89
	v_exp_f32_e32 v90, v90
	v_exp_f32_e32 v91, v91
	v_exp_f32_e32 v92, v92
	v_exp_f32_e32 v93, v93
	v_exp_f32_e32 v94, v94
	v_exp_f32_e32 v95, v95
	v_exp_f32_e32 v96, v96
	v_exp_f32_e32 v97, v97
	v_exp_f32_e32 v66, v66
	v_add_f32_e32 v244, v82, v83
	v_exp_f32_e32 v67, v67
	v_add_f32_e32 v244, v84, v244
	v_exp_f32_e32 v68, v68
	v_add_f32_e32 v244, v85, v244
	v_exp_f32_e32 v69, v69
	v_add_f32_e32 v244, v86, v244
	v_exp_f32_e32 v70, v70
	v_add_f32_e32 v244, v87, v244
	v_exp_f32_e32 v71, v71
	v_add_f32_e32 v244, v88, v244
	v_exp_f32_e32 v72, v72
	v_add_f32_e32 v244, v89, v244
	v_exp_f32_e32 v73, v73
	v_add_f32_e32 v244, v90, v244
	v_exp_f32_e32 v74, v74
	v_add_f32_e32 v244, v91, v244
	v_exp_f32_e32 v75, v75
	v_add_f32_e32 v244, v92, v244
	v_exp_f32_e32 v76, v76
	v_add_f32_e32 v244, v93, v244
	v_exp_f32_e32 v77, v77
	v_add_f32_e32 v244, v94, v244
	v_exp_f32_e32 v78, v78
	v_add_f32_e32 v244, v95, v244
	v_exp_f32_e32 v79, v79
	v_add_f32_e32 v244, v96, v244
	v_exp_f32_e32 v80, v80
	v_add_f32_e32 v244, v97, v244
	v_exp_f32_e32 v81, v81
	v_add_f32_e32 v249, v66, v67
	v_add_f32_e32 v249, v68, v249
	v_add_f32_e32 v249, v69, v249
	v_add_f32_e32 v249, v70, v249
	v_add_f32_e32 v249, v71, v249
	v_add_f32_e32 v249, v72, v249
	v_add_f32_e32 v249, v73, v249
	v_add_f32_e32 v249, v74, v249
	v_add_f32_e32 v249, v75, v249
	v_add_f32_e32 v249, v76, v249
	v_add_f32_e32 v249, v77, v249
	v_add_f32_e32 v249, v78, v249
	v_add_f32_e32 v249, v79, v249
	v_add_f32_e32 v249, v80, v249
	v_add_f32_e32 v249, v81, v249
	v_add_f32_e32 v244, v244, v249
	v_fma_f32 v238, v238, v248, v244
	v_cvt_pk_bf16_f32 v146, v82, v83
	v_cvt_pk_bf16_f32 v147, v84, v85
	v_cvt_pk_bf16_f32 v148, v86, v87
	v_cvt_pk_bf16_f32 v149, v88, v89
	v_cvt_pk_bf16_f32 v150, v90, v91
	v_cvt_pk_bf16_f32 v151, v92, v93
	v_cvt_pk_bf16_f32 v152, v94, v95
	v_cvt_pk_bf16_f32 v153, v96, v97
	v_cvt_pk_bf16_f32 v154, v66, v67
	v_cvt_pk_bf16_f32 v155, v68, v69
	v_cvt_pk_bf16_f32 v156, v70, v71
	v_cvt_pk_bf16_f32 v157, v72, v73
	v_cvt_pk_bf16_f32 v158, v74, v75
	v_cvt_pk_bf16_f32 v159, v76, v77
	v_cvt_pk_bf16_f32 v160, v78, v79
	v_cvt_pk_bf16_f32 v161, v80, v81
	s_add_i32 s40, s40, 1
	s_addk_i32 s65, 0x40
	v_add_u32_e32 v245, 0x100, v245
	s_barrier
	s_cmp_lt_u32 s40, 64
	s_cbranch_scc1 .Lat_loop
	s_add_i32 s54, s40, 3
	s_and_b32 s54, s54, 3
	s_lshl_b32 s54, s54, 14
	v_add_u32_e32 v244, s54, v225
	ds_read_b64_tr_b16 v[162:163], v244 offset:0x0
	ds_read_b64_tr_b16 v[164:165], v244 offset:0x800
	ds_read_b64_tr_b16 v[166:167], v244 offset:0x1000
	ds_read_b64_tr_b16 v[168:169], v244 offset:0x1800
	ds_read_b64_tr_b16 v[170:171], v244 offset:0x2000
	ds_read_b64_tr_b16 v[172:173], v244 offset:0x2800
	ds_read_b64_tr_b16 v[174:175], v244 offset:0x3000
	ds_read_b64_tr_b16 v[176:177], v244 offset:0x3800
	s_waitcnt lgkmcnt(0)
	v_mfma_f32_32x32x16_bf16 v[50:65], v[146:149], v[162:165], v[50:65]
	ds_read_b64_tr_b16 v[162:163], v244 offset:0x200
	ds_read_b64_tr_b16 v[164:165], v244 offset:0xa00
	v_mfma_f32_32x32x16_bf16 v[50:65], v[150:153], v[166:169], v[50:65]
	ds_read_b64_tr_b16 v[166:167], v244 offset:0x1200
	ds_read_b64_tr_b16 v[168:169], v244 offset:0x1a00
	v_mfma_f32_32x32x16_bf16 v[50:65], v[154:157], v[170:173], v[50:65]
	ds_read_b64_tr_b16 v[170:171], v244 offset:0x2200
	ds_read_b64_tr_b16 v[172:173], v244 offset:0x2a00
	v_mfma_f32_32x32x16_bf16 v[50:65], v[158:161], v[174:177], v[50:65]
	ds_read_b64_tr_b16 v[174:175], v244 offset:0x3200
	ds_read_b64_tr_b16 v[176:177], v244 offset:0x3a00
	s_waitcnt lgkmcnt(0)
	v_mfma_f32_32x32x16_bf16 v[34:49], v[146:149], v[162:165], v[34:49]
	ds_read_b64_tr_b16 v[162:163], v244 offset:0x400
	ds_read_b64_tr_b16 v[164:165], v244 offset:0xc00
	v_mfma_f32_32x32x16_bf16 v[34:49], v[150:153], v[166:169], v[34:49]
	ds_read_b64_tr_b16 v[166:167], v244 offset:0x1400
	ds_read_b64_tr_b16 v[168:169], v244 offset:0x1c00
	v_mfma_f32_32x32x16_bf16 v[34:49], v[154:157], v[170:173], v[34:49]
	ds_read_b64_tr_b16 v[170:171], v244 offset:0x2400
	ds_read_b64_tr_b16 v[172:173], v244 offset:0x2c00
	v_mfma_f32_32x32x16_bf16 v[34:49], v[158:161], v[174:177], v[34:49]
	ds_read_b64_tr_b16 v[174:175], v244 offset:0x3400
	ds_read_b64_tr_b16 v[176:177], v244 offset:0x3c00
	s_waitcnt lgkmcnt(0)
	v_mfma_f32_32x32x16_bf16 v[18:33], v[146:149], v[162:165], v[18:33]
	ds_read_b64_tr_b16 v[162:163], v244 offset:0x600
	ds_read_b64_tr_b16 v[164:165], v244 offset:0xe00
	v_mfma_f32_32x32x16_bf16 v[18:33], v[150:153], v[166:169], v[18:33]
	ds_read_b64_tr_b16 v[166:167], v244 offset:0x1600
	ds_read_b64_tr_b16 v[168:169], v244 offset:0x1e00
	v_mfma_f32_32x32x16_bf16 v[18:33], v[154:157], v[170:173], v[18:33]
	ds_read_b64_tr_b16 v[170:171], v244 offset:0x2600
	ds_read_b64_tr_b16 v[172:173], v244 offset:0x2e00
	v_mfma_f32_32x32x16_bf16 v[18:33], v[158:161], v[174:177], v[18:33]
	ds_read_b64_tr_b16 v[174:175], v244 offset:0x3600
	ds_read_b64_tr_b16 v[176:177], v244 offset:0x3e00
	s_waitcnt lgkmcnt(0)
	v_mfma_f32_32x32x16_bf16 v[2:17], v[146:149], v[162:165], v[2:17]
	v_mfma_f32_32x32x16_bf16 v[2:17], v[150:153], v[166:169], v[2:17]
	v_mfma_f32_32x32x16_bf16 v[2:17], v[154:157], v[170:173], v[2:17]
	v_mfma_f32_32x32x16_bf16 v[2:17], v[158:161], v[174:177], v[2:17]
	s_cmp_lg_u32 s67, 0
	s_cbranch_scc1 .Lat_fin
	s_barrier
